# grid barrier: XCD leader no longer bumps the unused per-XCD generation word
# baseline (speedup 1.0000x reference)
.LBB0_834:
	s_bcnt1_i32_b64 s4, s[4:5]
	v_mov_b32_e32 v0, s4
	s_getpc_b64 s[98:99]
